# NAT attention bias+mask section: the 16 per-element bias LDS reads issued together and masked with v_cndmask instead of 16 serialized exec-masked read/wait blocks
# speedup vs baseline: 1.0095x; 1.0095x over previous
.LBB0_510:
	s_lshl_b32 s72, s70, 14
	s_add_i32 s72, s72, 0
	v_add_u32_e32 v1, s72, v90
	v_add_u32_e32 v2, s72, v91
	ds_read_b128 v[28:31], v1
	ds_read_b128 v[32:35], v1 offset:2048
	ds_read_b128 v[36:39], v2
	ds_read_b128 v[40:43], v2 offset:2048
	ds_read_b128 v[44:47], v1 offset:4096
	ds_read_b128 v[48:51], v1 offset:6144
	ds_read_b128 v[52:55], v2 offset:4096
	ds_read_b128 v[56:59], v2 offset:6144
	s_waitcnt lgkmcnt(0)
	v_mfma_f32_16x16x32_bf16 v[28:31], v[28:31], v[4:7], 0
	v_add_u32_e32 v1, s72, v92
	v_add_u32_e32 v2, s72, v93
	v_mfma_f32_16x16x32_bf16 v[74:77], v[36:39], v[8:11], v[28:31]
	v_mfma_f32_16x16x32_bf16 v[28:31], v[32:35], v[4:7], 0
	v_mfma_f32_16x16x32_bf16 v[68:71], v[40:43], v[8:11], v[28:31]
	v_mfma_f32_16x16x32_bf16 v[28:31], v[44:47], v[4:7], 0
	v_mfma_f32_16x16x32_bf16 v[64:67], v[52:55], v[8:11], v[28:31]
	v_mfma_f32_16x16x32_bf16 v[28:31], v[48:51], v[4:7], 0
	v_mfma_f32_16x16x32_bf16 v[60:63], v[56:59], v[8:11], v[28:31]
	ds_read2st64_b64 v[56:59], v1 offset0:16 offset1:20
	ds_read2st64_b64 v[52:55], v2 offset0:16 offset1:20
	ds_read2st64_b64 v[48:51], v1 offset0:24 offset1:28
	ds_read2st64_b64 v[44:47], v2 offset0:24 offset1:28
	v_add_u32_e32 v1, s72, v96
	v_add_u32_e32 v2, s72, v97
	ds_read2st64_b64 v[40:43], v1 offset0:16 offset1:20
	ds_read2st64_b64 v[36:39], v2 offset0:16 offset1:20
	ds_read2st64_b64 v[32:35], v1 offset0:24 offset1:28
	ds_read2st64_b64 v[28:31], v2 offset0:24 offset1:28
	s_cmp_gt_u32 s71, 7
	s_mov_b32 s71, 0x3e38aa3b
	s_cbranch_scc1 .LBB0_544
	v_add_u32_e32 v1, s69, v98
	v_add_u32_e32 v1, 0x103a0, v1
	ds_read_b32 v102, v1
	ds_read_b32 v103, v1 offset:4
	ds_read_b32 v104, v1 offset:8
	ds_read_b32 v105, v1 offset:12
	ds_read_b32 v106, v1 offset:64
	ds_read_b32 v107, v1 offset:68
	ds_read_b32 v108, v1 offset:72
	ds_read_b32 v109, v1 offset:76
	ds_read_b32 v110, v1 offset:128
	ds_read_b32 v111, v1 offset:132
	ds_read_b32 v112, v1 offset:136
	ds_read_b32 v113, v1 offset:140
	ds_read_b32 v114, v1 offset:192
	ds_read_b32 v115, v1 offset:196
	ds_read_b32 v210, v1 offset:200
	ds_read_b32 v211, v1 offset:204
	v_mov_b32_e32 v2, 0xff800000
	s_mov_b32 s71, 1.0
	s_waitcnt lgkmcnt(15)
	v_mul_f32_e32 v3, s5, v102
	v_mul_f32_e32 v74, s4, v74
	v_add_f32_e32 v74, v74, v3
	v_cndmask_b32_e64 v74, v2, v74, s[40:41]
	s_waitcnt lgkmcnt(14)
	v_mul_f32_e32 v3, s5, v103
	v_mul_f32_e32 v75, s4, v75
	v_add_f32_e32 v75, v75, v3
	v_cndmask_b32_e64 v75, v2, v75, s[42:43]
	s_waitcnt lgkmcnt(13)
	v_mul_f32_e32 v3, s5, v104
	v_mul_f32_e32 v76, s4, v76
	v_add_f32_e32 v76, v76, v3
	v_cndmask_b32_e64 v76, v2, v76, s[44:45]
	s_waitcnt lgkmcnt(12)
	v_mul_f32_e32 v3, s5, v105
	v_mul_f32_e32 v77, s4, v77
	v_add_f32_e32 v77, v77, v3
	v_cndmask_b32_e64 v77, v2, v77, s[46:47]
	s_waitcnt lgkmcnt(11)
	v_mul_f32_e32 v3, s5, v106
	v_mul_f32_e32 v68, s4, v68
	v_add_f32_e32 v68, v68, v3
	v_cndmask_b32_e64 v68, v2, v68, s[28:29]
	s_waitcnt lgkmcnt(10)
	v_mul_f32_e32 v3, s5, v107
	v_mul_f32_e32 v69, s4, v69
	v_add_f32_e32 v69, v69, v3
	v_cndmask_b32_e64 v69, v2, v69, s[30:31]
	s_waitcnt lgkmcnt(9)
	v_mul_f32_e32 v3, s5, v108
	v_mul_f32_e32 v70, s4, v70
	v_add_f32_e32 v70, v70, v3
	v_cndmask_b32_e64 v70, v2, v70, s[34:35]
	s_waitcnt lgkmcnt(8)
	v_mul_f32_e32 v3, s5, v109
	v_mul_f32_e32 v71, s4, v71
	v_add_f32_e32 v71, v71, v3
	v_cndmask_b32_e64 v71, v2, v71, s[88:89]
	s_waitcnt lgkmcnt(7)
	v_mul_f32_e32 v3, s5, v110
	v_mul_f32_e32 v64, s4, v64
	v_add_f32_e32 v64, v64, v3
	v_cndmask_b32_e64 v64, v2, v64, s[12:13]
	s_waitcnt lgkmcnt(6)
	v_mul_f32_e32 v3, s5, v111
	v_mul_f32_e32 v65, s4, v65
	v_add_f32_e32 v65, v65, v3
	v_cndmask_b32_e64 v65, v2, v65, s[14:15]
	s_waitcnt lgkmcnt(5)
	v_mul_f32_e32 v3, s5, v112
	v_mul_f32_e32 v66, s4, v66
	v_add_f32_e32 v66, v66, v3
	v_cndmask_b32_e64 v66, v2, v66, s[60:61]
	s_waitcnt lgkmcnt(4)
	v_mul_f32_e32 v3, s5, v113
	v_mul_f32_e32 v67, s4, v67
	v_add_f32_e32 v67, v67, v3
	v_cndmask_b32_e64 v67, v2, v67, s[6:7]
	s_waitcnt lgkmcnt(3)
	v_mul_f32_e32 v3, s5, v114
	v_mul_f32_e32 v60, s4, v60
	v_add_f32_e32 v60, v60, v3
	v_cndmask_b32_e64 v60, v2, v60, s[48:49]
	s_waitcnt lgkmcnt(2)
	v_mul_f32_e32 v3, s5, v115
	v_mul_f32_e32 v61, s4, v61
	v_add_f32_e32 v61, v61, v3
	v_cndmask_b32_e64 v61, v2, v61, s[50:51]
	s_waitcnt lgkmcnt(1)
	v_mul_f32_e32 v3, s5, v210
	v_mul_f32_e32 v62, s4, v62
	v_add_f32_e32 v62, v62, v3
	v_cndmask_b32_e64 v62, v2, v62, s[52:53]
	s_waitcnt lgkmcnt(0)
	v_mul_f32_e32 v3, s5, v211
	v_mul_f32_e32 v63, s4, v63
	v_add_f32_e32 v63, v63, v3
	v_cndmask_b32_e64 v63, v2, v63, s[54:55]
